# waves 4-7 do their sgu row stage first and their token_prep copies (hand-written, loads up front) after it, overlapping waves 0-3's token_prep
# speedup vs baseline: 1.0114x; 1.0114x over previous
.LBB0_367:
	v_mov_b32_e32 v43, v186
	v_mov_b32_e32 v40, v186
	s_lshl_b32 s54, s52, 6
	s_waitcnt vmcnt(0)
	v_lshrrev_b32_e32 v0, 2, v40
	v_and_b32_e32 v41, 48, v0
	v_and_b32_e32 v154, 63, v43
	v_or_b32_e32 v153, s54, v41
	s_movk_i32 s0, 0xff
	v_lshlrev_b32_e32 v0, 5, v43
	s_ashr_i32 s53, s52, 5
	v_bfe_u32 v152, v153, 4, 7
	v_cmp_lt_u32_e32 vcc, s0, v40
	v_lshlrev_b32_e32 v156, 3, v154
	v_lshrrev_b32_e32 v42, 5, v153
	v_and_b32_e32 v155, 0xe0, v0
	s_and_saveexec_b64 s[0:1], vcc
	s_xor_b64 s[0:1], exec, s[0:1]
	s_cbranch_execz .LBB0_372
.LBB0_372:
	s_andn2_saveexec_b64 s[50:51], s[0:1]
	s_cbranch_execz .LBB0_366
	v_mov_b32_e32 v0, s54
	s_movk_i32 s0, 0x7f0
	v_lshlrev_b32_e32 v132, 5, v154
	v_mov_b32_e32 v133, v65
	v_bitop3_b32 v44, v41, s0, v0 bitop3:0xc8
	v_lshl_add_u64 v[32:33], s[42:43], 0, v[132:133]
	s_mov_b64 s[0:1], 0x1000
	s_waitcnt lgkmcnt(0)
	global_load_dwordx4 v[0:3], v155, s[34:35] offset:16
	global_load_dwordx4 v[4:7], v155, s[34:35]
	global_load_dwordx4 v[8:11], v155, s[40:41] offset:16
	global_load_dwordx4 v[12:15], v155, s[40:41]
	global_load_dwordx4 v[16:19], v132, s[42:43] offset:16
	global_load_dwordx4 v[20:23], v132, s[42:43]
	global_load_dwordx4 v[24:27], v132, s[42:43] offset:2064
	global_load_dwordx4 v[28:31], v132, s[42:43] offset:2048
	v_lshl_add_u64 v[36:37], v[32:33], 0, s[0:1]
	v_add_co_u32_e32 v32, vcc, 0x1000, v32
	v_mov_b32_e32 v64, v65
	s_nop 0
	v_addc_co_u32_e32 v33, vcc, 0, v33, vcc
	global_load_dwordx4 v[32:35], v[32:33], off
	s_nop 0
	global_load_dwordx4 v[36:39], v[36:37], off offset:16
	v_mov_b32_e32 v66, v65
	v_mov_b32_e32 v67, v65
	v_mov_b64_e32 v[90:91], v[66:67]
	v_mov_b64_e32 v[86:87], v[66:67]
	v_mov_b64_e32 v[70:71], v[66:67]
	v_mov_b64_e32 v[60:61], v[64:65]
	v_cmp_ne_u32_e32 vcc, 0, v44
	v_lshlrev_b32_e32 v134, 1, v156
	v_mov_b64_e32 v[88:89], v[64:65]
	v_mov_b64_e32 v[84:85], v[64:65]
	v_mov_b64_e32 v[68:69], v[64:65]
	v_mov_b64_e32 v[62:63], v[66:67]
	s_and_saveexec_b64 s[0:1], vcc
	s_cbranch_execz .LBB0_375
	v_add_u32_e32 v46, -1, v153
	v_mov_b64_e32 v[44:45], s[18:19]
	v_mad_i64_i32 v[46:47], s[2:3], v46, s66, v[44:45]
	v_mov_b32_e32 v135, v65
	v_lshl_add_u64 v[48:49], v[46:47], 0, v[134:135]
	v_add_u32_e32 v46, -2, v153
	v_mad_i64_i32 v[44:45], s[2:3], v46, s66, v[44:45]
	v_lshl_add_u64 v[56:57], v[44:45], 0, v[134:135]
	global_load_dwordx4 v[44:47], v[48:49], off offset:3632
	v_add_co_u32_e32 v48, vcc, 0x1000, v48
	s_waitcnt vmcnt(0)
	v_lshlrev_b32_e32 v60, 16, v44
	v_addc_co_u32_e32 v49, vcc, 0, v49, vcc
	global_load_dwordx4 v[48:51], v[48:49], off offset:560
	s_nop 0
	global_load_dwordx4 v[52:55], v[56:57], off offset:3632
	v_add_co_u32_e32 v56, vcc, 0x1000, v56
	v_and_b32_e32 v61, 0xffff0000, v44
	s_nop 0
	v_addc_co_u32_e32 v57, vcc, 0, v57, vcc
	global_load_dwordx4 v[56:59], v[56:57], off offset:560
	v_lshlrev_b32_e32 v44, 16, v45
	v_and_b32_e32 v45, 0xffff0000, v45
	v_lshlrev_b32_e32 v66, 16, v46
	v_and_b32_e32 v67, 0xffff0000, v46
	v_lshlrev_b32_e32 v46, 16, v47
	v_and_b32_e32 v47, 0xffff0000, v47
	s_waitcnt vmcnt(2)
	v_lshlrev_b32_e32 v68, 16, v48
	v_and_b32_e32 v69, 0xffff0000, v48
	v_lshlrev_b32_e32 v48, 16, v49
	v_and_b32_e32 v49, 0xffff0000, v49
	v_lshlrev_b32_e32 v72, 16, v50
	v_and_b32_e32 v73, 0xffff0000, v50
	v_lshlrev_b32_e32 v50, 16, v51
	v_and_b32_e32 v51, 0xffff0000, v51
	v_pk_mul_f32 v[62:63], v[44:45], v[48:49]
	v_pk_mul_f32 v[70:71], v[46:47], v[50:51]
	s_waitcnt vmcnt(1)
	v_lshlrev_b32_e32 v44, 16, v52
	v_and_b32_e32 v45, 0xffff0000, v52
	v_lshlrev_b32_e32 v46, 16, v53
	v_and_b32_e32 v47, 0xffff0000, v53
	v_lshlrev_b32_e32 v48, 16, v54
	v_and_b32_e32 v49, 0xffff0000, v54
	v_lshlrev_b32_e32 v50, 16, v55
	v_and_b32_e32 v51, 0xffff0000, v55
	s_waitcnt vmcnt(0)
	v_lshlrev_b32_e32 v52, 16, v56
	v_and_b32_e32 v53, 0xffff0000, v56
	v_lshlrev_b32_e32 v54, 16, v57
	v_and_b32_e32 v55, 0xffff0000, v57
	v_lshlrev_b32_e32 v56, 16, v58
	v_and_b32_e32 v57, 0xffff0000, v58
	v_lshlrev_b32_e32 v58, 16, v59
	v_and_b32_e32 v59, 0xffff0000, v59
	v_pk_mul_f32 v[60:61], v[60:61], v[68:69]
	v_pk_mul_f32 v[68:69], v[66:67], v[72:73]
	v_pk_mul_f32 v[86:87], v[46:47], v[54:55]
	v_pk_mul_f32 v[84:85], v[44:45], v[52:53]
	v_pk_mul_f32 v[90:91], v[50:51], v[58:59]
	v_pk_mul_f32 v[88:89], v[48:49], v[56:57]

.LBB0_437:
	s_or_b64 exec, exec, s[0:1]
	v_readfirstlane_b32 s3, v60
	s_cmpk_lt_u32 s3, 0x100
	s_cbranch_scc1 .Ltpdq_skip
	v_mov_b32_e32 v248, v60
	v_mov_b32_e32 v249, v66
	v_mov_b32_e32 v250, v68
	s_add_u32 s0, s54, 0x2a080000
	s_addc_u32 s1, s55, 0
	s_add_u32 s26, s54, 0x2b080000
	s_addc_u32 s27, s55, 0
	s_add_u32 s28, s54, 0x2c080000
	s_addc_u32 s29, s55, 0
	s_lshl_b32 vcc_lo, s84, 6
	s_lshr_b32 vcc_hi, s84, 5
	v_and_b32_e32 v177, 63, v186
	v_lshrrev_b32_e32 v179, 6, v186
	v_and_b32_e32 v179, 3, v179
	v_lshl_add_u32 v178, v179, 4, vcc_lo
	v_mul_u32_u24_e32 v183, s66, v178
	v_lshl_add_u32 v183, v177, 4, v183
	v_add_u32_e32 v183, 0x1e30, v183
	v_lshlrev_b32_e32 v174, 10, v178
	v_lshl_add_u32 v174, v177, 4, v174
	v_and_b32_e32 v180, 0x7ff, v178
	v_lshrrev_b32_e32 v181, 3, v177
	v_lshl_add_u32 v181, vcc_hi, 3, v181
	v_lshlrev_b32_e32 v181, 6, v181
	v_lshrrev_b32_e32 v182, 5, v180
	v_add_u32_e32 v181, v181, v182
	v_lshlrev_b32_e32 v175, 12, v181
	v_bfe_u32 v181, v177, 1, 2
	v_lshlrev_b32_e32 v181, 6, v181
	v_and_b32_e32 v182, 1, v177
	v_lshl_add_u32 v181, v182, 5, v181
	v_and_b32_e32 v182, 31, v180
	v_add_u32_e32 v181, v181, v182
	v_lshl_add_u32 v175, v181, 4, v175
	v_lshrrev_b32_e32 v181, 3, v177
	v_lshl_add_u32 v181, vcc_hi, 3, v181
	v_lshlrev_b32_e32 v181, 7, v181
	v_lshrrev_b32_e32 v182, 4, v180
	v_add_u32_e32 v181, v181, v182
	v_lshlrev_b32_e32 v181, 6, v181
	v_and_b32_e32 v182, 7, v177
	v_lshl_add_u32 v181, v182, 3, v181
	v_lshlrev_b32_e32 v176, 5, v181
	global_load_dwordx4 v[66:69], v183, s[18:19]
	global_load_dwordx4 v[130:133], v183, s[18:19] offset:1024
	v_add_u32_e32 v183, 0x2c00, v183
	global_load_dwordx4 v[70:73], v183, s[18:19]
	global_load_dwordx4 v[134:137], v183, s[18:19] offset:1024
	v_add_u32_e32 v183, 0x2c00, v183
	global_load_dwordx4 v[74:77], v183, s[18:19]
	global_load_dwordx4 v[138:141], v183, s[18:19] offset:1024
	v_add_u32_e32 v183, 0x2c00, v183
	global_load_dwordx4 v[78:81], v183, s[18:19]
	global_load_dwordx4 v[150:153], v183, s[18:19] offset:1024
	v_add_u32_e32 v183, 0x2c00, v183
	global_load_dwordx4 v[82:85], v183, s[18:19]
	global_load_dwordx4 v[154:157], v183, s[18:19] offset:1024
	v_add_u32_e32 v183, 0x2c00, v183
	global_load_dwordx4 v[86:89], v183, s[18:19]
	global_load_dwordx4 v[158:161], v183, s[18:19] offset:1024
	v_add_u32_e32 v183, 0x2c00, v183
	global_load_dwordx4 v[90:93], v183, s[18:19]
	global_load_dwordx4 v[200:203], v183, s[18:19] offset:1024
	v_add_u32_e32 v183, 0x2c00, v183
	global_load_dwordx4 v[94:97], v183, s[18:19]
	global_load_dwordx4 v[204:207], v183, s[18:19] offset:1024
	v_add_u32_e32 v183, 0x2c00, v183
	global_load_dwordx4 v[98:101], v183, s[18:19]
	global_load_dwordx4 v[208:211], v183, s[18:19] offset:1024
	v_add_u32_e32 v183, 0x2c00, v183
	global_load_dwordx4 v[102:105], v183, s[18:19]
	global_load_dwordx4 v[212:215], v183, s[18:19] offset:1024
	v_add_u32_e32 v183, 0x2c00, v183
	global_load_dwordx4 v[106:109], v183, s[18:19]
	global_load_dwordx4 v[216:219], v183, s[18:19] offset:1024
	v_add_u32_e32 v183, 0x2c00, v183
	global_load_dwordx4 v[110:113], v183, s[18:19]
	global_load_dwordx4 v[220:223], v183, s[18:19] offset:1024
	v_add_u32_e32 v183, 0x2c00, v183
	global_load_dwordx4 v[114:117], v183, s[18:19]
	global_load_dwordx4 v[224:227], v183, s[18:19] offset:1024
	v_add_u32_e32 v183, 0x2c00, v183
	global_load_dwordx4 v[118:121], v183, s[18:19]
	global_load_dwordx4 v[228:231], v183, s[18:19] offset:1024
	v_add_u32_e32 v183, 0x2c00, v183
	global_load_dwordx4 v[122:125], v183, s[18:19]
	global_load_dwordx4 v[232:235], v183, s[18:19] offset:1024
	v_add_u32_e32 v183, 0x2c00, v183
	global_load_dwordx4 v[126:129], v183, s[18:19]
	global_load_dwordx4 v[236:239], v183, s[18:19] offset:1024
	v_subrev_u32_e32 v183, 0x29400, v183
	global_load_dwordx4 v[0:3], v183, s[18:19] offset:2048
	v_add_u32_e32 v183, 0x2c00, v183
	global_load_dwordx4 v[4:7], v183, s[18:19] offset:2048
	v_add_u32_e32 v183, 0x2c00, v183
	global_load_dwordx4 v[8:11], v183, s[18:19] offset:2048
	v_add_u32_e32 v183, 0x2c00, v183
	global_load_dwordx4 v[12:15], v183, s[18:19] offset:2048
	v_add_u32_e32 v183, 0x2c00, v183
	global_load_dwordx4 v[16:19], v183, s[18:19] offset:2048
	v_add_u32_e32 v183, 0x2c00, v183
	global_load_dwordx4 v[20:23], v183, s[18:19] offset:2048
	v_add_u32_e32 v183, 0x2c00, v183
	global_load_dwordx4 v[24:27], v183, s[18:19] offset:2048
	v_add_u32_e32 v183, 0x2c00, v183
	global_load_dwordx4 v[28:31], v183, s[18:19] offset:2048
	v_add_u32_e32 v183, 0x2c00, v183
	global_load_dwordx4 v[32:35], v183, s[18:19] offset:2048
	v_add_u32_e32 v183, 0x2c00, v183
	global_load_dwordx4 v[36:39], v183, s[18:19] offset:2048
	v_add_u32_e32 v183, 0x2c00, v183
	global_load_dwordx4 v[40:43], v183, s[18:19] offset:2048
	v_add_u32_e32 v183, 0x2c00, v183
	global_load_dwordx4 v[44:47], v183, s[18:19] offset:2048
	v_add_u32_e32 v183, 0x2c00, v183
	global_load_dwordx4 v[48:51], v183, s[18:19] offset:2048
	v_add_u32_e32 v183, 0x2c00, v183
	global_load_dwordx4 v[52:55], v183, s[18:19] offset:2048
	v_add_u32_e32 v183, 0x2c00, v183
	global_load_dwordx4 v[56:59], v183, s[18:19] offset:2048
	v_add_u32_e32 v183, 0x2c00, v183
	global_load_dwordx4 v[60:63], v183, s[18:19] offset:2048
	s_mov_b32 s2, 0x05040100
	s_mov_b32 s3, 0x07060302
	s_waitcnt vmcnt(46)
	v_lshlrev_b32_e32 v179, 16, v66
	v_and_b32_e32 v180, 0xffff0000, v66
	v_mul_f32_e32 v179, 0.125, v179
	v_mul_f32_e32 v180, 0.125, v180
	v_cvt_pk_bf16_f32 v66, v179, v180
	v_lshlrev_b32_e32 v179, 16, v67
	v_and_b32_e32 v180, 0xffff0000, v67
	v_mul_f32_e32 v179, 0.125, v179
	v_mul_f32_e32 v180, 0.125, v180
	v_cvt_pk_bf16_f32 v67, v179, v180
	v_lshlrev_b32_e32 v179, 16, v68
	v_and_b32_e32 v180, 0xffff0000, v68
	v_mul_f32_e32 v179, 0.125, v179
	v_mul_f32_e32 v180, 0.125, v180
	v_cvt_pk_bf16_f32 v68, v179, v180
	v_lshlrev_b32_e32 v179, 16, v69
	v_and_b32_e32 v180, 0xffff0000, v69
	v_mul_f32_e32 v179, 0.125, v179
	v_mul_f32_e32 v180, 0.125, v180
	v_cvt_pk_bf16_f32 v69, v179, v180
	v_mov_b32_e32 v182, v174
	global_store_dwordx4 v182, v[66:69], s[0:1]
	global_store_dwordx4 v175, v[130:133], s[26:27]
	s_waitcnt vmcnt(46)
	v_lshlrev_b32_e32 v179, 16, v70
	v_and_b32_e32 v180, 0xffff0000, v70
	v_mul_f32_e32 v179, 0.125, v179
	v_mul_f32_e32 v180, 0.125, v180
	v_cvt_pk_bf16_f32 v70, v179, v180
	v_lshlrev_b32_e32 v179, 16, v71
	v_and_b32_e32 v180, 0xffff0000, v71
	v_mul_f32_e32 v179, 0.125, v179
	v_mul_f32_e32 v180, 0.125, v180
	v_cvt_pk_bf16_f32 v71, v179, v180
	v_lshlrev_b32_e32 v179, 16, v72
	v_and_b32_e32 v180, 0xffff0000, v72
	v_mul_f32_e32 v179, 0.125, v179
	v_mul_f32_e32 v180, 0.125, v180
	v_cvt_pk_bf16_f32 v72, v179, v180
	v_lshlrev_b32_e32 v179, 16, v73
	v_and_b32_e32 v180, 0xffff0000, v73
	v_mul_f32_e32 v179, 0.125, v179
	v_mul_f32_e32 v180, 0.125, v180
	v_cvt_pk_bf16_f32 v73, v179, v180
	v_add_u32_e32 v181, 0x400, v174
	global_store_dwordx4 v181, v[70:73], s[0:1]
	global_store_dwordx4 v175, v[134:137], s[26:27] offset:16
	s_waitcnt vmcnt(46)
	v_lshlrev_b32_e32 v179, 16, v74
	v_and_b32_e32 v180, 0xffff0000, v74
	v_mul_f32_e32 v179, 0.125, v179
	v_mul_f32_e32 v180, 0.125, v180
	v_cvt_pk_bf16_f32 v74, v179, v180
	v_lshlrev_b32_e32 v179, 16, v75
	v_and_b32_e32 v180, 0xffff0000, v75
	v_mul_f32_e32 v179, 0.125, v179
	v_mul_f32_e32 v180, 0.125, v180
	v_cvt_pk_bf16_f32 v75, v179, v180
	v_lshlrev_b32_e32 v179, 16, v76
	v_and_b32_e32 v180, 0xffff0000, v76
	v_mul_f32_e32 v179, 0.125, v179
	v_mul_f32_e32 v180, 0.125, v180
	v_cvt_pk_bf16_f32 v76, v179, v180
	v_lshlrev_b32_e32 v179, 16, v77
	v_and_b32_e32 v180, 0xffff0000, v77
	v_mul_f32_e32 v179, 0.125, v179
	v_mul_f32_e32 v180, 0.125, v180
	v_cvt_pk_bf16_f32 v77, v179, v180
	v_add_u32_e32 v182, 0x800, v174
	global_store_dwordx4 v182, v[74:77], s[0:1]
	global_store_dwordx4 v175, v[138:141], s[26:27] offset:32
	s_waitcnt vmcnt(46)
	v_lshlrev_b32_e32 v179, 16, v78
	v_and_b32_e32 v180, 0xffff0000, v78
	v_mul_f32_e32 v179, 0.125, v179
	v_mul_f32_e32 v180, 0.125, v180
	v_cvt_pk_bf16_f32 v78, v179, v180
	v_lshlrev_b32_e32 v179, 16, v79
	v_and_b32_e32 v180, 0xffff0000, v79
	v_mul_f32_e32 v179, 0.125, v179
	v_mul_f32_e32 v180, 0.125, v180
	v_cvt_pk_bf16_f32 v79, v179, v180
	v_lshlrev_b32_e32 v179, 16, v80
	v_and_b32_e32 v180, 0xffff0000, v80
	v_mul_f32_e32 v179, 0.125, v179
	v_mul_f32_e32 v180, 0.125, v180
	v_cvt_pk_bf16_f32 v80, v179, v180
	v_lshlrev_b32_e32 v179, 16, v81
	v_and_b32_e32 v180, 0xffff0000, v81
	v_mul_f32_e32 v179, 0.125, v179
	v_mul_f32_e32 v180, 0.125, v180
	v_cvt_pk_bf16_f32 v81, v179, v180
	v_add_u32_e32 v181, 0xc00, v174
	global_store_dwordx4 v181, v[78:81], s[0:1]
	global_store_dwordx4 v175, v[150:153], s[26:27] offset:48
	s_waitcnt vmcnt(46)
	v_lshlrev_b32_e32 v179, 16, v82
	v_and_b32_e32 v180, 0xffff0000, v82
	v_mul_f32_e32 v179, 0.125, v179
	v_mul_f32_e32 v180, 0.125, v180
	v_cvt_pk_bf16_f32 v82, v179, v180
	v_lshlrev_b32_e32 v179, 16, v83
	v_and_b32_e32 v180, 0xffff0000, v83
	v_mul_f32_e32 v179, 0.125, v179
	v_mul_f32_e32 v180, 0.125, v180
	v_cvt_pk_bf16_f32 v83, v179, v180
	v_lshlrev_b32_e32 v179, 16, v84
	v_and_b32_e32 v180, 0xffff0000, v84
	v_mul_f32_e32 v179, 0.125, v179
	v_mul_f32_e32 v180, 0.125, v180
	v_cvt_pk_bf16_f32 v84, v179, v180
	v_lshlrev_b32_e32 v179, 16, v85
	v_and_b32_e32 v180, 0xffff0000, v85
	v_mul_f32_e32 v179, 0.125, v179
	v_mul_f32_e32 v180, 0.125, v180
	v_cvt_pk_bf16_f32 v85, v179, v180
	v_add_u32_e32 v182, 0x1000, v174
	global_store_dwordx4 v182, v[82:85], s[0:1]
	global_store_dwordx4 v175, v[154:157], s[26:27] offset:64
	s_waitcnt vmcnt(46)
	v_lshlrev_b32_e32 v179, 16, v86
	v_and_b32_e32 v180, 0xffff0000, v86
	v_mul_f32_e32 v179, 0.125, v179
	v_mul_f32_e32 v180, 0.125, v180
	v_cvt_pk_bf16_f32 v86, v179, v180
	v_lshlrev_b32_e32 v179, 16, v87
	v_and_b32_e32 v180, 0xffff0000, v87
	v_mul_f32_e32 v179, 0.125, v179
	v_mul_f32_e32 v180, 0.125, v180
	v_cvt_pk_bf16_f32 v87, v179, v180
	v_lshlrev_b32_e32 v179, 16, v88
	v_and_b32_e32 v180, 0xffff0000, v88
	v_mul_f32_e32 v179, 0.125, v179
	v_mul_f32_e32 v180, 0.125, v180
	v_cvt_pk_bf16_f32 v88, v179, v180
	v_lshlrev_b32_e32 v179, 16, v89
	v_and_b32_e32 v180, 0xffff0000, v89
	v_mul_f32_e32 v179, 0.125, v179
	v_mul_f32_e32 v180, 0.125, v180
	v_cvt_pk_bf16_f32 v89, v179, v180
	v_add_u32_e32 v181, 0x1400, v174
	global_store_dwordx4 v181, v[86:89], s[0:1]
	global_store_dwordx4 v175, v[158:161], s[26:27] offset:80
	s_waitcnt vmcnt(46)
	v_lshlrev_b32_e32 v179, 16, v90
	v_and_b32_e32 v180, 0xffff0000, v90
	v_mul_f32_e32 v179, 0.125, v179
	v_mul_f32_e32 v180, 0.125, v180
	v_cvt_pk_bf16_f32 v90, v179, v180
	v_lshlrev_b32_e32 v179, 16, v91
	v_and_b32_e32 v180, 0xffff0000, v91
	v_mul_f32_e32 v179, 0.125, v179
	v_mul_f32_e32 v180, 0.125, v180
	v_cvt_pk_bf16_f32 v91, v179, v180
	v_lshlrev_b32_e32 v179, 16, v92
	v_and_b32_e32 v180, 0xffff0000, v92
	v_mul_f32_e32 v179, 0.125, v179
	v_mul_f32_e32 v180, 0.125, v180
	v_cvt_pk_bf16_f32 v92, v179, v180
	v_lshlrev_b32_e32 v179, 16, v93
	v_and_b32_e32 v180, 0xffff0000, v93
	v_mul_f32_e32 v179, 0.125, v179
	v_mul_f32_e32 v180, 0.125, v180
	v_cvt_pk_bf16_f32 v93, v179, v180
	v_add_u32_e32 v182, 0x1800, v174
	global_store_dwordx4 v182, v[90:93], s[0:1]
	global_store_dwordx4 v175, v[200:203], s[26:27] offset:96
	s_waitcnt vmcnt(46)
	v_lshlrev_b32_e32 v179, 16, v94
	v_and_b32_e32 v180, 0xffff0000, v94
	v_mul_f32_e32 v179, 0.125, v179
	v_mul_f32_e32 v180, 0.125, v180
	v_cvt_pk_bf16_f32 v94, v179, v180
	v_lshlrev_b32_e32 v179, 16, v95
	v_and_b32_e32 v180, 0xffff0000, v95
	v_mul_f32_e32 v179, 0.125, v179
	v_mul_f32_e32 v180, 0.125, v180
	v_cvt_pk_bf16_f32 v95, v179, v180
	v_lshlrev_b32_e32 v179, 16, v96
	v_and_b32_e32 v180, 0xffff0000, v96
	v_mul_f32_e32 v179, 0.125, v179
	v_mul_f32_e32 v180, 0.125, v180
	v_cvt_pk_bf16_f32 v96, v179, v180
	v_lshlrev_b32_e32 v179, 16, v97
	v_and_b32_e32 v180, 0xffff0000, v97
	v_mul_f32_e32 v179, 0.125, v179
	v_mul_f32_e32 v180, 0.125, v180
	v_cvt_pk_bf16_f32 v97, v179, v180
	v_add_u32_e32 v181, 0x1c00, v174
	global_store_dwordx4 v181, v[94:97], s[0:1]
	global_store_dwordx4 v175, v[204:207], s[26:27] offset:112
	s_waitcnt vmcnt(46)
	v_lshlrev_b32_e32 v179, 16, v98
	v_and_b32_e32 v180, 0xffff0000, v98
	v_mul_f32_e32 v179, 0.125, v179
	v_mul_f32_e32 v180, 0.125, v180
	v_cvt_pk_bf16_f32 v98, v179, v180
	v_lshlrev_b32_e32 v179, 16, v99
	v_and_b32_e32 v180, 0xffff0000, v99
	v_mul_f32_e32 v179, 0.125, v179
	v_mul_f32_e32 v180, 0.125, v180
	v_cvt_pk_bf16_f32 v99, v179, v180
	v_lshlrev_b32_e32 v179, 16, v100
	v_and_b32_e32 v180, 0xffff0000, v100
	v_mul_f32_e32 v179, 0.125, v179
	v_mul_f32_e32 v180, 0.125, v180
	v_cvt_pk_bf16_f32 v100, v179, v180
	v_lshlrev_b32_e32 v179, 16, v101
	v_and_b32_e32 v180, 0xffff0000, v101
	v_mul_f32_e32 v179, 0.125, v179
	v_mul_f32_e32 v180, 0.125, v180
	v_cvt_pk_bf16_f32 v101, v179, v180
	v_add_u32_e32 v182, 0x2000, v174
	global_store_dwordx4 v182, v[98:101], s[0:1]
	global_store_dwordx4 v175, v[208:211], s[26:27] offset:128
	s_waitcnt vmcnt(46)
	v_lshlrev_b32_e32 v179, 16, v102
	v_and_b32_e32 v180, 0xffff0000, v102
	v_mul_f32_e32 v179, 0.125, v179
	v_mul_f32_e32 v180, 0.125, v180
	v_cvt_pk_bf16_f32 v102, v179, v180
	v_lshlrev_b32_e32 v179, 16, v103
	v_and_b32_e32 v180, 0xffff0000, v103
	v_mul_f32_e32 v179, 0.125, v179
	v_mul_f32_e32 v180, 0.125, v180
	v_cvt_pk_bf16_f32 v103, v179, v180
	v_lshlrev_b32_e32 v179, 16, v104
	v_and_b32_e32 v180, 0xffff0000, v104
	v_mul_f32_e32 v179, 0.125, v179
	v_mul_f32_e32 v180, 0.125, v180
	v_cvt_pk_bf16_f32 v104, v179, v180
	v_lshlrev_b32_e32 v179, 16, v105
	v_and_b32_e32 v180, 0xffff0000, v105
	v_mul_f32_e32 v179, 0.125, v179
	v_mul_f32_e32 v180, 0.125, v180
	v_cvt_pk_bf16_f32 v105, v179, v180
	v_add_u32_e32 v181, 0x2400, v174
	global_store_dwordx4 v181, v[102:105], s[0:1]
	global_store_dwordx4 v175, v[212:215], s[26:27] offset:144
	s_waitcnt vmcnt(46)
	v_lshlrev_b32_e32 v179, 16, v106
	v_and_b32_e32 v180, 0xffff0000, v106
	v_mul_f32_e32 v179, 0.125, v179
	v_mul_f32_e32 v180, 0.125, v180
	v_cvt_pk_bf16_f32 v106, v179, v180
	v_lshlrev_b32_e32 v179, 16, v107
	v_and_b32_e32 v180, 0xffff0000, v107
	v_mul_f32_e32 v179, 0.125, v179
	v_mul_f32_e32 v180, 0.125, v180
	v_cvt_pk_bf16_f32 v107, v179, v180
	v_lshlrev_b32_e32 v179, 16, v108
	v_and_b32_e32 v180, 0xffff0000, v108
	v_mul_f32_e32 v179, 0.125, v179
	v_mul_f32_e32 v180, 0.125, v180
	v_cvt_pk_bf16_f32 v108, v179, v180
	v_lshlrev_b32_e32 v179, 16, v109
	v_and_b32_e32 v180, 0xffff0000, v109
	v_mul_f32_e32 v179, 0.125, v179
	v_mul_f32_e32 v180, 0.125, v180
	v_cvt_pk_bf16_f32 v109, v179, v180
	v_add_u32_e32 v182, 0x2800, v174
	global_store_dwordx4 v182, v[106:109], s[0:1]
	global_store_dwordx4 v175, v[216:219], s[26:27] offset:160
	s_waitcnt vmcnt(46)
	v_lshlrev_b32_e32 v179, 16, v110
	v_and_b32_e32 v180, 0xffff0000, v110
	v_mul_f32_e32 v179, 0.125, v179
	v_mul_f32_e32 v180, 0.125, v180
	v_cvt_pk_bf16_f32 v110, v179, v180
	v_lshlrev_b32_e32 v179, 16, v111
	v_and_b32_e32 v180, 0xffff0000, v111
	v_mul_f32_e32 v179, 0.125, v179
	v_mul_f32_e32 v180, 0.125, v180
	v_cvt_pk_bf16_f32 v111, v179, v180
	v_lshlrev_b32_e32 v179, 16, v112
	v_and_b32_e32 v180, 0xffff0000, v112
	v_mul_f32_e32 v179, 0.125, v179
	v_mul_f32_e32 v180, 0.125, v180
	v_cvt_pk_bf16_f32 v112, v179, v180
	v_lshlrev_b32_e32 v179, 16, v113
	v_and_b32_e32 v180, 0xffff0000, v113
	v_mul_f32_e32 v179, 0.125, v179
	v_mul_f32_e32 v180, 0.125, v180
	v_cvt_pk_bf16_f32 v113, v179, v180
	v_add_u32_e32 v181, 0x2c00, v174
	global_store_dwordx4 v181, v[110:113], s[0:1]
	global_store_dwordx4 v175, v[220:223], s[26:27] offset:176
	s_waitcnt vmcnt(46)
	v_lshlrev_b32_e32 v179, 16, v114
	v_and_b32_e32 v180, 0xffff0000, v114
	v_mul_f32_e32 v179, 0.125, v179
	v_mul_f32_e32 v180, 0.125, v180
	v_cvt_pk_bf16_f32 v114, v179, v180
	v_lshlrev_b32_e32 v179, 16, v115
	v_and_b32_e32 v180, 0xffff0000, v115
	v_mul_f32_e32 v179, 0.125, v179
	v_mul_f32_e32 v180, 0.125, v180
	v_cvt_pk_bf16_f32 v115, v179, v180
	v_lshlrev_b32_e32 v179, 16, v116
	v_and_b32_e32 v180, 0xffff0000, v116
	v_mul_f32_e32 v179, 0.125, v179
	v_mul_f32_e32 v180, 0.125, v180
	v_cvt_pk_bf16_f32 v116, v179, v180
	v_lshlrev_b32_e32 v179, 16, v117
	v_and_b32_e32 v180, 0xffff0000, v117
	v_mul_f32_e32 v179, 0.125, v179
	v_mul_f32_e32 v180, 0.125, v180
	v_cvt_pk_bf16_f32 v117, v179, v180
	v_add_u32_e32 v182, 0x3000, v174
	global_store_dwordx4 v182, v[114:117], s[0:1]
	global_store_dwordx4 v175, v[224:227], s[26:27] offset:192
	s_waitcnt vmcnt(46)
	v_lshlrev_b32_e32 v179, 16, v118
	v_and_b32_e32 v180, 0xffff0000, v118
	v_mul_f32_e32 v179, 0.125, v179
	v_mul_f32_e32 v180, 0.125, v180
	v_cvt_pk_bf16_f32 v118, v179, v180
	v_lshlrev_b32_e32 v179, 16, v119
	v_and_b32_e32 v180, 0xffff0000, v119
	v_mul_f32_e32 v179, 0.125, v179
	v_mul_f32_e32 v180, 0.125, v180
	v_cvt_pk_bf16_f32 v119, v179, v180
	v_lshlrev_b32_e32 v179, 16, v120
	v_and_b32_e32 v180, 0xffff0000, v120
	v_mul_f32_e32 v179, 0.125, v179
	v_mul_f32_e32 v180, 0.125, v180
	v_cvt_pk_bf16_f32 v120, v179, v180
	v_lshlrev_b32_e32 v179, 16, v121
	v_and_b32_e32 v180, 0xffff0000, v121
	v_mul_f32_e32 v179, 0.125, v179
	v_mul_f32_e32 v180, 0.125, v180
	v_cvt_pk_bf16_f32 v121, v179, v180
	v_add_u32_e32 v181, 0x3400, v174
	global_store_dwordx4 v181, v[118:121], s[0:1]
	global_store_dwordx4 v175, v[228:231], s[26:27] offset:208
	s_waitcnt vmcnt(46)
	v_lshlrev_b32_e32 v179, 16, v122
	v_and_b32_e32 v180, 0xffff0000, v122
	v_mul_f32_e32 v179, 0.125, v179
	v_mul_f32_e32 v180, 0.125, v180
	v_cvt_pk_bf16_f32 v122, v179, v180
	v_lshlrev_b32_e32 v179, 16, v123
	v_and_b32_e32 v180, 0xffff0000, v123
	v_mul_f32_e32 v179, 0.125, v179
	v_mul_f32_e32 v180, 0.125, v180
	v_cvt_pk_bf16_f32 v123, v179, v180
	v_lshlrev_b32_e32 v179, 16, v124
	v_and_b32_e32 v180, 0xffff0000, v124
	v_mul_f32_e32 v179, 0.125, v179
	v_mul_f32_e32 v180, 0.125, v180
	v_cvt_pk_bf16_f32 v124, v179, v180
	v_lshlrev_b32_e32 v179, 16, v125
	v_and_b32_e32 v180, 0xffff0000, v125
	v_mul_f32_e32 v179, 0.125, v179
	v_mul_f32_e32 v180, 0.125, v180
	v_cvt_pk_bf16_f32 v125, v179, v180
	v_add_u32_e32 v182, 0x3800, v174
	global_store_dwordx4 v182, v[122:125], s[0:1]
	global_store_dwordx4 v175, v[232:235], s[26:27] offset:224
	s_waitcnt vmcnt(46)
	v_lshlrev_b32_e32 v179, 16, v126
	v_and_b32_e32 v180, 0xffff0000, v126
	v_mul_f32_e32 v179, 0.125, v179
	v_mul_f32_e32 v180, 0.125, v180
	v_cvt_pk_bf16_f32 v126, v179, v180
	v_lshlrev_b32_e32 v179, 16, v127
	v_and_b32_e32 v180, 0xffff0000, v127
	v_mul_f32_e32 v179, 0.125, v179
	v_mul_f32_e32 v180, 0.125, v180
	v_cvt_pk_bf16_f32 v127, v179, v180
	v_lshlrev_b32_e32 v179, 16, v128
	v_and_b32_e32 v180, 0xffff0000, v128
	v_mul_f32_e32 v179, 0.125, v179
	v_mul_f32_e32 v180, 0.125, v180
	v_cvt_pk_bf16_f32 v128, v179, v180
	v_lshlrev_b32_e32 v179, 16, v129
	v_and_b32_e32 v180, 0xffff0000, v129
	v_mul_f32_e32 v179, 0.125, v179
	v_mul_f32_e32 v180, 0.125, v180
	v_cvt_pk_bf16_f32 v129, v179, v180
	v_add_u32_e32 v181, 0x3c00, v174
	global_store_dwordx4 v181, v[126:129], s[0:1]
	global_store_dwordx4 v175, v[236:239], s[26:27] offset:240
	s_waitcnt vmcnt(32)
	s_nop 1
	v_perm_b32 v66, v4, v0, s2
	v_perm_b32 v67, v12, v8, s2
	v_perm_b32 v68, v36, v32, s2
	v_perm_b32 v69, v44, v40, s2
	v_perm_b32 v70, v20, v16, s2
	v_perm_b32 v71, v28, v24, s2
	v_perm_b32 v72, v52, v48, s2
	v_perm_b32 v73, v60, v56, s2
	global_store_dwordx4 v176, v[66:69], s[28:29]
	global_store_dwordx4 v176, v[70:73], s[28:29] offset:16
	v_perm_b32 v74, v4, v0, s3
	v_perm_b32 v75, v12, v8, s3
	v_perm_b32 v76, v36, v32, s3
	v_perm_b32 v77, v44, v40, s3
	v_perm_b32 v78, v20, v16, s3
	v_perm_b32 v79, v28, v24, s3
	v_perm_b32 v80, v52, v48, s3
	v_perm_b32 v81, v60, v56, s3
	global_store_dwordx4 v176, v[74:77], s[28:29] offset:32
	global_store_dwordx4 v176, v[78:81], s[28:29] offset:48
	v_perm_b32 v66, v5, v1, s2
	v_perm_b32 v67, v13, v9, s2
	v_perm_b32 v68, v37, v33, s2
	v_perm_b32 v69, v45, v41, s2
	v_perm_b32 v70, v21, v17, s2
	v_perm_b32 v71, v29, v25, s2
	v_perm_b32 v72, v53, v49, s2
	v_perm_b32 v73, v61, v57, s2
	global_store_dwordx4 v176, v[66:69], s[28:29] offset:64
	global_store_dwordx4 v176, v[70:73], s[28:29] offset:80
	v_perm_b32 v74, v5, v1, s3
	v_perm_b32 v75, v13, v9, s3
	v_perm_b32 v76, v37, v33, s3
	v_perm_b32 v77, v45, v41, s3
	v_perm_b32 v78, v21, v17, s3
	v_perm_b32 v79, v29, v25, s3
	v_perm_b32 v80, v53, v49, s3
	v_perm_b32 v81, v61, v57, s3
	global_store_dwordx4 v176, v[74:77], s[28:29] offset:96
	global_store_dwordx4 v176, v[78:81], s[28:29] offset:112
	v_perm_b32 v66, v6, v2, s2
	v_perm_b32 v67, v14, v10, s2
	v_perm_b32 v68, v38, v34, s2
	v_perm_b32 v69, v46, v42, s2
	v_perm_b32 v70, v22, v18, s2
	v_perm_b32 v71, v30, v26, s2
	v_perm_b32 v72, v54, v50, s2
	v_perm_b32 v73, v62, v58, s2
	global_store_dwordx4 v176, v[66:69], s[28:29] offset:128
	global_store_dwordx4 v176, v[70:73], s[28:29] offset:144
	v_perm_b32 v74, v6, v2, s3
	v_perm_b32 v75, v14, v10, s3
	v_perm_b32 v76, v38, v34, s3
	v_perm_b32 v77, v46, v42, s3
	v_perm_b32 v78, v22, v18, s3
	v_perm_b32 v79, v30, v26, s3
	v_perm_b32 v80, v54, v50, s3
	v_perm_b32 v81, v62, v58, s3
	global_store_dwordx4 v176, v[74:77], s[28:29] offset:160
	global_store_dwordx4 v176, v[78:81], s[28:29] offset:176
	v_perm_b32 v66, v7, v3, s2
	v_perm_b32 v67, v15, v11, s2
	v_perm_b32 v68, v39, v35, s2
	v_perm_b32 v69, v47, v43, s2
	v_perm_b32 v70, v23, v19, s2
	v_perm_b32 v71, v31, v27, s2
	v_perm_b32 v72, v55, v51, s2
	v_perm_b32 v73, v63, v59, s2
	global_store_dwordx4 v176, v[66:69], s[28:29] offset:192
	global_store_dwordx4 v176, v[70:73], s[28:29] offset:208
	v_perm_b32 v74, v7, v3, s3
	v_perm_b32 v75, v15, v11, s3
	v_perm_b32 v76, v39, v35, s3
	v_perm_b32 v77, v47, v43, s3
	v_perm_b32 v78, v23, v19, s3
	v_perm_b32 v79, v31, v27, s3
	v_perm_b32 v80, v55, v51, s3
	v_perm_b32 v81, v63, v59, s3
	global_store_dwordx4 v176, v[74:77], s[28:29] offset:224
	global_store_dwordx4 v176, v[78:81], s[28:29] offset:240
	v_mov_b32_e32 v60, v248
	v_mov_b32_e32 v66, v249
	v_mov_b32_e32 v68, v250
.Ltpdq_skip:
	s_lshr_b32 s0, s30, 3
	v_bfe_u32 v70, v60, 6, 2
	v_and_b32_e32 v82, 31, v66
	s_and_b32 s0, s0, 1
	v_ashrrev_i32_e32 v67, 8, v60
	v_lshlrev_b32_e32 v0, 3, v68
	v_lshl_or_b32 v1, v70, 6, v82
	v_lshl_add_u32 v3, v68, 4, 0
	v_mov_b32_e32 v63, 0
	s_lshl_b32 s2, s0, 2
	v_lshlrev_b32_e32 v69, 6, v67
	v_cmp_lt_i32_e32 vcc, -1, v67
	v_mad_u32_u24 v71, v1, s86, v3
	v_or_b32_e32 v72, 16, v0
	v_mov_b32_e32 v62, v63
	v_mov_b32_e32 v61, v63
	v_mov_b32_e32 v60, v63
	v_mov_b32_e32 v59, v63
	v_mov_b32_e32 v58, v63
	v_mov_b32_e32 v57, v63
	v_mov_b32_e32 v56, v63
	v_mov_b32_e32 v55, v63
	v_mov_b32_e32 v54, v63
	v_mov_b32_e32 v53, v63
	v_mov_b32_e32 v52, v63
	v_mov_b32_e32 v51, v63
	v_mov_b32_e32 v50, v63
	v_mov_b32_e32 v49, v63
	v_mov_b32_e32 v48, v63
	v_mov_b32_e32 v47, v63
	v_mov_b32_e32 v46, v63
	v_mov_b32_e32 v45, v63
	v_mov_b32_e32 v44, v63
	v_mov_b32_e32 v43, v63
	v_mov_b32_e32 v42, v63
	v_mov_b32_e32 v41, v63
	v_mov_b32_e32 v40, v63
	v_mov_b32_e32 v39, v63
	v_mov_b32_e32 v38, v63
	v_mov_b32_e32 v37, v63
	v_mov_b32_e32 v36, v63
	v_mov_b32_e32 v35, v63
	v_mov_b32_e32 v34, v63
	v_mov_b32_e32 v33, v63
	v_mov_b32_e32 v32, v63
	s_add_i32 s3, s21, s2
	v_add_u32_e32 v216, s3, v70
	v_lshlrev_b32_e32 v216, 16, v216
	v_add_u32_e32 v220, v69, v82
	v_lshl_add_u32 v216, v220, 9, v216
	v_and_b32_e32 v221, 32, v66
	v_add_u32_e32 v216, v216, v221
	v_mov_b32_e32 v217, 0
	v_lshl_add_u64 v[216:217], s[24:25], 0, v[216:217]
	s_mov_b64 s[26:27], 0x4000
	v_lshl_add_u64 v[218:219], v[216:217], 0, s[26:27]
	v_lshlrev_b32_e32 v220, 3, v68
	v_sub_u32_e32 v220, v82, v220
	v_add_u32_e32 v221, -16, v220
	v_readfirstlane_b32 s3, v67
	s_cmp_eq_u32 s3, 0
	s_cbranch_scc0 .Lsgu2_issue1
	global_load_dwordx4 v[88:91], v[216:217], off offset:-64
	global_load_dwordx4 v[92:95], v[216:217], off offset:-48
	global_load_dwordx4 v[96:99], v[216:217], off offset:0
	global_load_dwordx4 v[100:103], v[216:217], off offset:16
	global_load_dwordx4 v[104:107], v[218:219], off offset:-64
	global_load_dwordx4 v[108:111], v[218:219], off offset:-48
	global_load_dwordx4 v[112:115], v[218:219], off offset:0
	global_load_dwordx4 v[116:119], v[218:219], off offset:16
	global_load_dwordx4 v[120:123], v[218:219], off offset:64
	global_load_dwordx4 v[124:127], v[218:219], off offset:80
	global_load_dwordx4 v[128:131], v[218:219], off offset:128
	global_load_dwordx4 v[132:135], v[218:219], off offset:144
	s_branch .Lsgu2_issued
